# RWKV loader waves' code 8-byte aligned too (VOP1/VOP2 re-encoded as VOP3, s_nop partners for single 4-byte instructions)
# baseline (speedup 1.0000x reference)
; #define LAS __attribute__((address_space(3)))
; #define RW_LOAD(c) do { RW_LOAD1(c, 0); RW_LOAD1(c, 1); } while (0)
; #define RW_PROC(dst) do { RW_PROC1(dst, 0); RW_PROC1(dst, 1); } while (0)
; template <bool SAMPLE>
; __device__ __forceinline__ void rwkv_unit(PR P, LAS float* lds, const int b, const int h, const int half, const int wv) {
;     ...
;     RW_LOAD(0); RW_PROC(buf0); __syncthreads();
;     for (int c = 0; c < NCH; ++c) {
;         LAS float* cur = (c & 1) ? buf1 : buf0; LAS float* nxt = (c & 1) ? buf0 : buf1;
;         if (c + 1 < NCH) RW_LOAD(c + 1);
.LBB0_702:
	s_or_b64 exec, exec, s[8:9]
	v_ashrrev_i32_e32 v57, 6, v56
	s_lshl_b32 s8, s2, 5
	v_lshlrev_b32_e32 v21, 3, v57
	v_lshrrev_b32_e32 v56, 3, v54
	s_and_b32 s8, s8, 32
	v_and_b32_e32 v21, 24, v21
	v_and_b32_e32 v56, 6, v56
	v_and_b32_e32 v66, 15, v54
	v_or3_b32 v54, v56, s8, v21
	v_mov_b32_e32 v56, 0
	v_mov_b32_e32 v21, v56
	v_lshl_add_u64 v[58:59], s[12:13], 0, v[20:21]
	v_lshl_add_u64 v[60:61], s[10:11], 0, v[20:21]
	v_lshl_add_u64 v[62:63], s[14:15], 0, v[20:21]
	v_lshlrev_b32_e32 v20, 1, v54
	s_mov_b32 s71, 0
	v_lshl_add_u64 v[20:21], s[46:47], 0, v[20:21]
	s_lshl_b32 s70, s20, 1
	v_lshl_add_u64 v[20:21], v[20:21], 0, s[70:71]
	s_mov_b64 s[12:13], 0xbae4800
	v_lshlrev_b32_e32 v76, 2, v66
	v_cmp_gt_i32_e64 s[8:9], 4, v57
	v_or_b32_e32 v77, s6, v66
	v_lshl_add_u64 v[64:65], v[20:21], 0, s[12:13]
	v_and_b32_e32 v72, 3, v66
	v_cmp_eq_u32_e64 s[12:13], 0, v72
	v_cmp_eq_u32_e64 s[14:15], 1, v72
	v_cmp_eq_u32_e64 s[16:17], 2, v72
	s_movk_i32 s49, 0x1e00
	s_add_i32 s55, 0, 0xc000
	v_mov_b32_e32 v66, 0
	v_mov_b32_e32 v67, v56
	v_mov_b32_e32 v20, v56
	v_mov_b32_e32 v21, v56
	v_mov_b32_e32 v68, v56
	v_mov_b32_e32 v69, v56
	v_mov_b32_e32 v70, v56
	v_mov_b32_e32 v71, v56
	.p2alignl 3, 3212836864
	s_add_u32 s18, s46, 0x3d44800
	s_addc_u32 s19, s47, 0
	s_nop 0
	s_sub_u32 s20, s18, 0x1e00
	s_subb_u32 s21, s19, 0
	s_nop 0
	s_add_u32 s22, s46, 0xda04800
	s_addc_u32 s23, s47, 0
	s_nop 0
	s_add_u32 s24, s46, 0xea84800
	s_addc_u32 s25, s47, 0
	s_nop 0
	s_bfe_u32 s26, s2, 0x30001
	s_lshl_b32 s26, s26, 7
	s_nop 0
	v_lshrrev_b32_e64 v123, 1, v75
	v_add_u32_e64 v123, s26, v123
	v_mul_u32_u24_e32 v121, 0x1e00, v55
	v_add_u32_e64 v121, v121, v123
	v_lshl_add_u32 v122, v55, 10, v123
	v_add_u32_e64 v123, v74, v75
	s_cmp_lt_u32 s33, 0x100
	s_cbranch_scc1 .Lld_noprefetch
	s_mov_b32 s29, 1
	s_lshl_b32 s26, s29, 5
	s_add_i32 s26, s26, s6
	s_mul_i32 s27, s26, 0x1e00
	s_lshl_b32 s28, s26, 10
	s_nop 0
	v_add_u32_e64 v78, s27, v121
	v_add_u32_e64 v79, s28, v122
	global_load_dwordx2 v[124:125], v78, s[18:19]
	global_load_dwordx2 v[126:127], v78, s[18:19] offset:1024
	global_load_dwordx2 v[128:129], v78, s[18:19] offset:2048
	global_load_dwordx2 v[130:131], v78, s[20:21]
	global_load_dwordx2 v[132:133], v78, s[20:21] offset:1024
	global_load_dwordx2 v[134:135], v78, s[20:21] offset:2048
	global_load_dwordx2 v[136:137], v79, s[22:23]
	global_load_dwordx2 v[138:139], v79, s[24:25]
	s_add_u32 s27, s27, 0x1e000
	s_add_u32 s28, s28, 0x4000
	v_add_u32_e64 v80, s27, v121
	v_add_u32_e64 v81, s28, v122
	global_load_dwordx2 v[140:141], v80, s[18:19]
	global_load_dwordx2 v[142:143], v80, s[18:19] offset:1024
	global_load_dwordx2 v[144:145], v80, s[18:19] offset:2048
	global_load_dwordx2 v[146:147], v80, s[20:21]
	global_load_dwordx2 v[148:149], v80, s[20:21] offset:1024
	global_load_dwordx2 v[150:151], v80, s[20:21] offset:2048
	global_load_dwordx2 v[152:153], v81, s[22:23]
	global_load_dwordx2 v[154:155], v81, s[24:25]
	.p2alignl 3, 3212836864
.Lld_noprefetch:
	s_waitcnt lgkmcnt(0)
	s_barrier
	s_branch .LBB0_705
	.p2alignl 3, 3212836864
.LBB0_704:
	s_cmp_eq_u32 s56, 64
	s_mov_b32 s71, s56
	s_waitcnt lgkmcnt(0)
	s_barrier
	s_cbranch_scc1 .LBB0_723
	.p2alignl 3, 3212836864
.LBB0_705:
	s_cmp_lt_u32 s33, 0x100
	s_cbranch_scc1 .Lrw_scan_chunk
	s_add_i32 s56, s71, 1
	s_cmp_eq_u32 s71, 63
	s_cbranch_scc1 .LBB0_704
	s_add_i32 s29, s56, 1
	s_bitcmp1_b32 s71, 0
	s_cbranch_scc1 .Lld_odd
	s_cmp_lt_u32 s29, 64
	s_cbranch_scc0 .Lld_last_even
	s_lshl_b32 s26, s29, 5
	s_add_i32 s26, s26, s6
	s_nop 0
	s_mul_i32 s27, s26, 0x1e00
	s_lshl_b32 s28, s26, 10
	s_nop 0
	v_add_u32_e64 v78, s27, v121
	v_add_u32_e64 v79, s28, v122
	global_load_dwordx2 v[22:23], v78, s[18:19]
	global_load_dwordx2 v[24:25], v78, s[18:19] offset:1024
	global_load_dwordx2 v[26:27], v78, s[18:19] offset:2048
	global_load_dwordx2 v[28:29], v78, s[20:21]
	global_load_dwordx2 v[30:31], v78, s[20:21] offset:1024
	global_load_dwordx2 v[32:33], v78, s[20:21] offset:2048
	global_load_dwordx2 v[34:35], v79, s[22:23]
	global_load_dwordx2 v[36:37], v79, s[24:25]
	s_add_u32 s27, s27, 0x1e000
	s_add_u32 s28, s28, 0x4000
	v_add_u32_e64 v80, s27, v121
	v_add_u32_e64 v81, s28, v122
	global_load_dwordx2 v[38:39], v80, s[18:19]
	global_load_dwordx2 v[40:41], v80, s[18:19] offset:1024
	global_load_dwordx2 v[42:43], v80, s[18:19] offset:2048
	global_load_dwordx2 v[44:45], v80, s[20:21]
	global_load_dwordx2 v[46:47], v80, s[20:21] offset:1024
	global_load_dwordx2 v[48:49], v80, s[20:21] offset:2048
	global_load_dwordx2 v[50:51], v81, s[22:23]
	global_load_dwordx2 v[52:53], v81, s[24:25]
	s_waitcnt vmcnt(16)
	s_branch .Lld_go_even
	.p2alignl 3, 3212836864
.Lld_last_even:
	s_waitcnt vmcnt(0)
	.p2alignl 3, 3212836864
.Lld_go_even:
	s_bitcmp0_b32 s71, 0
	s_nop 0
	s_cselect_b32 s26, 0xc000, 0
	v_add_u32_e64 v80, s26, v123
	v_lshlrev_b32_e64 v104, 16, v124
	v_and_b32_e32 v105, 0xffff0000, v124
	v_lshlrev_b32_e64 v106, 16, v125
	v_and_b32_e32 v107, 0xffff0000, v125
	v_lshlrev_b32_e64 v108, 16, v130
	v_and_b32_e32 v109, 0xffff0000, v130
	v_lshlrev_b32_e64 v110, 16, v131
	v_and_b32_e32 v111, 0xffff0000, v131
	v_pk_add_f32 v[108:109], v[108:109], v[104:105] neg_lo:[0,1] neg_hi:[0,1]
	v_pk_add_f32 v[110:111], v[110:111], v[106:107] neg_lo:[0,1] neg_hi:[0,1]
	v_pk_fma_f32 v[84:85], v[0:1], v[108:109], v[104:105]
	v_pk_fma_f32 v[86:87], v[2:3], v[110:111], v[106:107]
	v_lshlrev_b32_e64 v104, 16, v126
	v_and_b32_e32 v105, 0xffff0000, v126
	v_lshlrev_b32_e64 v106, 16, v127
	v_and_b32_e32 v107, 0xffff0000, v127
	v_lshlrev_b32_e64 v108, 16, v132
	v_and_b32_e32 v109, 0xffff0000, v132
	v_lshlrev_b32_e64 v110, 16, v133
	v_and_b32_e32 v111, 0xffff0000, v133
	v_pk_add_f32 v[108:109], v[108:109], v[104:105] neg_lo:[0,1] neg_hi:[0,1]
	v_pk_add_f32 v[110:111], v[110:111], v[106:107] neg_lo:[0,1] neg_hi:[0,1]
	v_pk_fma_f32 v[88:89], v[12:13], v[108:109], v[104:105]
	v_pk_fma_f32 v[90:91], v[14:15], v[110:111], v[106:107]
	v_lshlrev_b32_e64 v104, 16, v128
	v_and_b32_e32 v105, 0xffff0000, v128
	v_lshlrev_b32_e64 v106, 16, v129
	v_and_b32_e32 v107, 0xffff0000, v129
	v_lshlrev_b32_e64 v108, 16, v134
	v_and_b32_e32 v109, 0xffff0000, v134
	v_lshlrev_b32_e64 v110, 16, v135
	v_and_b32_e32 v111, 0xffff0000, v135
	v_pk_add_f32 v[108:109], v[108:109], v[104:105] neg_lo:[0,1] neg_hi:[0,1]
	v_pk_add_f32 v[110:111], v[110:111], v[106:107] neg_lo:[0,1] neg_hi:[0,1]
	v_pk_fma_f32 v[92:93], v[4:5], v[108:109], v[104:105]
	v_pk_fma_f32 v[94:95], v[6:7], v[110:111], v[106:107]
	v_lshlrev_b32_e64 v96, 16, v136
	v_and_b32_e32 v97, 0xffff0000, v136
	v_lshlrev_b32_e64 v98, 16, v137
	v_and_b32_e32 v99, 0xffff0000, v137
	v_lshlrev_b32_e64 v100, 16, v138
	v_and_b32_e32 v101, 0xffff0000, v138
	v_lshlrev_b32_e64 v102, 16, v139
	v_and_b32_e32 v103, 0xffff0000, v139
	v_pk_mul_f32 v[112:113], v[8:9], v[88:89]
	v_pk_mul_f32 v[114:115], v[10:11], v[90:91]
	v_pk_mul_f32 v[104:105], v[112:113], v[112:113]
	v_pk_fma_f32 v[104:105], v[114:115], v[114:115], v[104:105]
	v_add_f32_e64 v104, v104, v105
	v_pk_add_f32 v[116:117], v[100:101], -1.0 op_sel_hi:[1,0]
	v_pk_add_f32 v[118:119], v[102:103], -1.0 op_sel_hi:[1,0]
	v_add_f32_dpp v104, v104, v104 quad_perm:[1,0,3,2] row_mask:0xf bank_mask:0xf bound_ctrl:1
	v_pk_fma_f32 v[116:117], v[16:17], v[116:117], 1.0 op_sel_hi:[1,1,0]
	v_pk_fma_f32 v[118:119], v[18:19], v[118:119], 1.0 op_sel_hi:[1,1,0]
	v_add_f32_dpp v104, v104, v104 quad_perm:[2,3,0,1] row_mask:0xf bank_mask:0xf bound_ctrl:1
	v_pk_mul_f32 v[116:117], v[116:117], v[88:89]
	v_pk_mul_f32 v[118:119], v[118:119], v[90:91]
	v_add_f32_dpp v104, v104, v104 row_half_mirror row_mask:0xf bank_mask:0xf bound_ctrl:1
	ds_write_b128 v80, v[84:87] offset:0
	ds_write_b128 v80, v[96:99] offset:256
	v_add_f32_dpp v104, v104, v104 row_mirror row_mask:0xf bank_mask:0xf bound_ctrl:1
	v_rsq_f32_e64 v104, v104
	ds_write_b128 v80, v[116:119] offset:512
	v_min_f32_e32 v104, 0x5368d4a5, v104
	v_pk_mul_f32 v[112:113], v[112:113], v[104:105] op_sel_hi:[1,0] neg_lo:[0,1] neg_hi:[0,1]
	v_pk_mul_f32 v[114:115], v[114:115], v[104:105] op_sel_hi:[1,0] neg_lo:[0,1] neg_hi:[0,1]
	ds_write_b128 v80, v[112:115] offset:768
	v_pk_mul_f32 v[108:109], v[112:113], v[100:101] neg_lo:[1,0] neg_hi:[1,0]
	v_pk_mul_f32 v[110:111], v[114:115], v[102:103] neg_lo:[1,0] neg_hi:[1,0]
	ds_write_b128 v80, v[108:111] offset:1024
	ds_write_b128 v80, v[92:95] offset:1280
	v_lshlrev_b32_e64 v104, 16, v140
	v_and_b32_e32 v105, 0xffff0000, v140
	v_lshlrev_b32_e64 v106, 16, v141
	v_and_b32_e32 v107, 0xffff0000, v141
	v_lshlrev_b32_e64 v108, 16, v146
	v_and_b32_e32 v109, 0xffff0000, v146
	v_lshlrev_b32_e64 v110, 16, v147
	v_and_b32_e32 v111, 0xffff0000, v147
	v_pk_add_f32 v[108:109], v[108:109], v[104:105] neg_lo:[0,1] neg_hi:[0,1]
	v_pk_add_f32 v[110:111], v[110:111], v[106:107] neg_lo:[0,1] neg_hi:[0,1]
	v_pk_fma_f32 v[84:85], v[0:1], v[108:109], v[104:105]
	v_pk_fma_f32 v[86:87], v[2:3], v[110:111], v[106:107]
	v_lshlrev_b32_e64 v104, 16, v142
	v_and_b32_e32 v105, 0xffff0000, v142
	v_lshlrev_b32_e64 v106, 16, v143
	v_and_b32_e32 v107, 0xffff0000, v143
	v_lshlrev_b32_e64 v108, 16, v148
	v_and_b32_e32 v109, 0xffff0000, v148
	v_lshlrev_b32_e64 v110, 16, v149
	v_and_b32_e32 v111, 0xffff0000, v149
	v_pk_add_f32 v[108:109], v[108:109], v[104:105] neg_lo:[0,1] neg_hi:[0,1]
	v_pk_add_f32 v[110:111], v[110:111], v[106:107] neg_lo:[0,1] neg_hi:[0,1]
	v_pk_fma_f32 v[88:89], v[12:13], v[108:109], v[104:105]
	v_pk_fma_f32 v[90:91], v[14:15], v[110:111], v[106:107]
	v_lshlrev_b32_e64 v104, 16, v144
	v_and_b32_e32 v105, 0xffff0000, v144
	v_lshlrev_b32_e64 v106, 16, v145
	v_and_b32_e32 v107, 0xffff0000, v145
	v_lshlrev_b32_e64 v108, 16, v150
	v_and_b32_e32 v109, 0xffff0000, v150
	v_lshlrev_b32_e64 v110, 16, v151
	v_and_b32_e32 v111, 0xffff0000, v151
	v_pk_add_f32 v[108:109], v[108:109], v[104:105] neg_lo:[0,1] neg_hi:[0,1]
	v_pk_add_f32 v[110:111], v[110:111], v[106:107] neg_lo:[0,1] neg_hi:[0,1]
	v_pk_fma_f32 v[92:93], v[4:5], v[108:109], v[104:105]
	v_pk_fma_f32 v[94:95], v[6:7], v[110:111], v[106:107]
	v_lshlrev_b32_e64 v96, 16, v152
	v_and_b32_e32 v97, 0xffff0000, v152
	v_lshlrev_b32_e64 v98, 16, v153
	v_and_b32_e32 v99, 0xffff0000, v153
	v_lshlrev_b32_e64 v100, 16, v154
	v_and_b32_e32 v101, 0xffff0000, v154
	v_lshlrev_b32_e64 v102, 16, v155
	v_and_b32_e32 v103, 0xffff0000, v155
	v_pk_mul_f32 v[112:113], v[8:9], v[88:89]
	v_pk_mul_f32 v[114:115], v[10:11], v[90:91]
	v_pk_mul_f32 v[104:105], v[112:113], v[112:113]
	v_pk_fma_f32 v[104:105], v[114:115], v[114:115], v[104:105]
	v_add_f32_e64 v104, v104, v105
	v_pk_add_f32 v[116:117], v[100:101], -1.0 op_sel_hi:[1,0]
	v_pk_add_f32 v[118:119], v[102:103], -1.0 op_sel_hi:[1,0]
	v_add_f32_dpp v104, v104, v104 quad_perm:[1,0,3,2] row_mask:0xf bank_mask:0xf bound_ctrl:1
	v_pk_fma_f32 v[116:117], v[16:17], v[116:117], 1.0 op_sel_hi:[1,1,0]
	v_pk_fma_f32 v[118:119], v[18:19], v[118:119], 1.0 op_sel_hi:[1,1,0]
	v_add_f32_dpp v104, v104, v104 quad_perm:[2,3,0,1] row_mask:0xf bank_mask:0xf bound_ctrl:1
	v_pk_mul_f32 v[116:117], v[116:117], v[88:89]
	v_pk_mul_f32 v[118:119], v[118:119], v[90:91]
	v_add_f32_dpp v104, v104, v104 row_half_mirror row_mask:0xf bank_mask:0xf bound_ctrl:1
	ds_write_b128 v80, v[84:87] offset:24576
	ds_write_b128 v80, v[96:99] offset:24832
	v_add_f32_dpp v104, v104, v104 row_mirror row_mask:0xf bank_mask:0xf bound_ctrl:1
	v_rsq_f32_e64 v104, v104
	ds_write_b128 v80, v[116:119] offset:25088
	v_min_f32_e32 v104, 0x5368d4a5, v104
	v_pk_mul_f32 v[112:113], v[112:113], v[104:105] op_sel_hi:[1,0] neg_lo:[0,1] neg_hi:[0,1]
	v_pk_mul_f32 v[114:115], v[114:115], v[104:105] op_sel_hi:[1,0] neg_lo:[0,1] neg_hi:[0,1]
	ds_write_b128 v80, v[112:115] offset:25344
	v_pk_mul_f32 v[108:109], v[112:113], v[100:101] neg_lo:[1,0] neg_hi:[1,0]
	v_pk_mul_f32 v[110:111], v[114:115], v[102:103] neg_lo:[1,0] neg_hi:[1,0]
	ds_write_b128 v80, v[108:111] offset:25600
	ds_write_b128 v80, v[92:95] offset:25856
	s_branch .LBB0_704
	.p2alignl 3, 3212836864
.Lld_odd:
	s_cmp_lt_u32 s29, 64
	s_cbranch_scc0 .Lld_last_odd
	s_lshl_b32 s26, s29, 5
	s_add_i32 s26, s26, s6
	s_mul_i32 s27, s26, 0x1e00
	s_lshl_b32 s28, s26, 10
	s_nop 0
	v_add_u32_e64 v78, s27, v121
	v_add_u32_e64 v79, s28, v122
	global_load_dwordx2 v[124:125], v78, s[18:19]
	global_load_dwordx2 v[126:127], v78, s[18:19] offset:1024
	global_load_dwordx2 v[128:129], v78, s[18:19] offset:2048
	global_load_dwordx2 v[130:131], v78, s[20:21]
	global_load_dwordx2 v[132:133], v78, s[20:21] offset:1024
	global_load_dwordx2 v[134:135], v78, s[20:21] offset:2048
	global_load_dwordx2 v[136:137], v79, s[22:23]
	global_load_dwordx2 v[138:139], v79, s[24:25]
	s_add_u32 s27, s27, 0x1e000
	s_add_u32 s28, s28, 0x4000
	v_add_u32_e64 v80, s27, v121
	v_add_u32_e64 v81, s28, v122
	global_load_dwordx2 v[140:141], v80, s[18:19]
	global_load_dwordx2 v[142:143], v80, s[18:19] offset:1024
	global_load_dwordx2 v[144:145], v80, s[18:19] offset:2048
	global_load_dwordx2 v[146:147], v80, s[20:21]
	global_load_dwordx2 v[148:149], v80, s[20:21] offset:1024
	global_load_dwordx2 v[150:151], v80, s[20:21] offset:2048
	global_load_dwordx2 v[152:153], v81, s[22:23]
	global_load_dwordx2 v[154:155], v81, s[24:25]
	s_waitcnt vmcnt(16)
	s_branch .Lld_go_odd
	.p2alignl 3, 3212836864

.Lld_go_odd:
	s_bitcmp0_b32 s71, 0
	s_nop 0
	s_cselect_b32 s26, 0xc000, 0
	v_add_u32_e64 v80, s26, v123
	v_lshlrev_b32_e64 v104, 16, v22
	v_and_b32_e32 v105, 0xffff0000, v22
	v_lshlrev_b32_e64 v106, 16, v23
	v_and_b32_e32 v107, 0xffff0000, v23
	v_lshlrev_b32_e64 v108, 16, v28
	v_and_b32_e32 v109, 0xffff0000, v28
	v_lshlrev_b32_e64 v110, 16, v29
	v_and_b32_e32 v111, 0xffff0000, v29
	v_pk_add_f32 v[108:109], v[108:109], v[104:105] neg_lo:[0,1] neg_hi:[0,1]
	v_pk_add_f32 v[110:111], v[110:111], v[106:107] neg_lo:[0,1] neg_hi:[0,1]
	v_pk_fma_f32 v[84:85], v[0:1], v[108:109], v[104:105]
	v_pk_fma_f32 v[86:87], v[2:3], v[110:111], v[106:107]
	v_lshlrev_b32_e64 v104, 16, v24
	v_and_b32_e32 v105, 0xffff0000, v24
	v_lshlrev_b32_e64 v106, 16, v25
	v_and_b32_e32 v107, 0xffff0000, v25
	v_lshlrev_b32_e64 v108, 16, v30
	v_and_b32_e32 v109, 0xffff0000, v30
	v_lshlrev_b32_e64 v110, 16, v31
	v_and_b32_e32 v111, 0xffff0000, v31
	v_pk_add_f32 v[108:109], v[108:109], v[104:105] neg_lo:[0,1] neg_hi:[0,1]
	v_pk_add_f32 v[110:111], v[110:111], v[106:107] neg_lo:[0,1] neg_hi:[0,1]
	v_pk_fma_f32 v[88:89], v[12:13], v[108:109], v[104:105]
	v_pk_fma_f32 v[90:91], v[14:15], v[110:111], v[106:107]
	v_lshlrev_b32_e64 v104, 16, v26
	v_and_b32_e32 v105, 0xffff0000, v26
	v_lshlrev_b32_e64 v106, 16, v27
	v_and_b32_e32 v107, 0xffff0000, v27
	v_lshlrev_b32_e64 v108, 16, v32
	v_and_b32_e32 v109, 0xffff0000, v32
	v_lshlrev_b32_e64 v110, 16, v33
	v_and_b32_e32 v111, 0xffff0000, v33
	v_pk_add_f32 v[108:109], v[108:109], v[104:105] neg_lo:[0,1] neg_hi:[0,1]
	v_pk_add_f32 v[110:111], v[110:111], v[106:107] neg_lo:[0,1] neg_hi:[0,1]
	v_pk_fma_f32 v[92:93], v[4:5], v[108:109], v[104:105]
	v_pk_fma_f32 v[94:95], v[6:7], v[110:111], v[106:107]
	v_lshlrev_b32_e64 v96, 16, v34
	v_and_b32_e32 v97, 0xffff0000, v34
	v_lshlrev_b32_e64 v98, 16, v35
	v_and_b32_e32 v99, 0xffff0000, v35
	v_lshlrev_b32_e64 v100, 16, v36
	v_and_b32_e32 v101, 0xffff0000, v36
	v_lshlrev_b32_e64 v102, 16, v37
	v_and_b32_e32 v103, 0xffff0000, v37
	v_pk_mul_f32 v[112:113], v[8:9], v[88:89]
	v_pk_mul_f32 v[114:115], v[10:11], v[90:91]
	v_pk_mul_f32 v[104:105], v[112:113], v[112:113]
	v_pk_fma_f32 v[104:105], v[114:115], v[114:115], v[104:105]
	v_add_f32_e64 v104, v104, v105
	v_pk_add_f32 v[116:117], v[100:101], -1.0 op_sel_hi:[1,0]
	v_pk_add_f32 v[118:119], v[102:103], -1.0 op_sel_hi:[1,0]
	v_add_f32_dpp v104, v104, v104 quad_perm:[1,0,3,2] row_mask:0xf bank_mask:0xf bound_ctrl:1
	v_pk_fma_f32 v[116:117], v[16:17], v[116:117], 1.0 op_sel_hi:[1,1,0]
	v_pk_fma_f32 v[118:119], v[18:19], v[118:119], 1.0 op_sel_hi:[1,1,0]
	v_add_f32_dpp v104, v104, v104 quad_perm:[2,3,0,1] row_mask:0xf bank_mask:0xf bound_ctrl:1
	v_pk_mul_f32 v[116:117], v[116:117], v[88:89]
	v_pk_mul_f32 v[118:119], v[118:119], v[90:91]
	v_add_f32_dpp v104, v104, v104 row_half_mirror row_mask:0xf bank_mask:0xf bound_ctrl:1
	ds_write_b128 v80, v[84:87] offset:0
	ds_write_b128 v80, v[96:99] offset:256
	v_add_f32_dpp v104, v104, v104 row_mirror row_mask:0xf bank_mask:0xf bound_ctrl:1
	v_rsq_f32_e64 v104, v104
	ds_write_b128 v80, v[116:119] offset:512
	v_min_f32_e32 v104, 0x5368d4a5, v104
	v_pk_mul_f32 v[112:113], v[112:113], v[104:105] op_sel_hi:[1,0] neg_lo:[0,1] neg_hi:[0,1]
	v_pk_mul_f32 v[114:115], v[114:115], v[104:105] op_sel_hi:[1,0] neg_lo:[0,1] neg_hi:[0,1]
	ds_write_b128 v80, v[112:115] offset:768
	v_pk_mul_f32 v[108:109], v[112:113], v[100:101] neg_lo:[1,0] neg_hi:[1,0]
	v_pk_mul_f32 v[110:111], v[114:115], v[102:103] neg_lo:[1,0] neg_hi:[1,0]
	ds_write_b128 v80, v[108:111] offset:1024
	ds_write_b128 v80, v[92:95] offset:1280
	v_lshlrev_b32_e64 v104, 16, v38
	v_and_b32_e32 v105, 0xffff0000, v38
	v_lshlrev_b32_e64 v106, 16, v39
	v_and_b32_e32 v107, 0xffff0000, v39
	v_lshlrev_b32_e64 v108, 16, v44
	v_and_b32_e32 v109, 0xffff0000, v44
	v_lshlrev_b32_e64 v110, 16, v45
	v_and_b32_e32 v111, 0xffff0000, v45
	v_pk_add_f32 v[108:109], v[108:109], v[104:105] neg_lo:[0,1] neg_hi:[0,1]
	v_pk_add_f32 v[110:111], v[110:111], v[106:107] neg_lo:[0,1] neg_hi:[0,1]
	v_pk_fma_f32 v[84:85], v[0:1], v[108:109], v[104:105]
	v_pk_fma_f32 v[86:87], v[2:3], v[110:111], v[106:107]
	v_lshlrev_b32_e64 v104, 16, v40
	v_and_b32_e32 v105, 0xffff0000, v40
	v_lshlrev_b32_e64 v106, 16, v41
	v_and_b32_e32 v107, 0xffff0000, v41
	v_lshlrev_b32_e64 v108, 16, v46
	v_and_b32_e32 v109, 0xffff0000, v46
	v_lshlrev_b32_e64 v110, 16, v47
	v_and_b32_e32 v111, 0xffff0000, v47
	v_pk_add_f32 v[108:109], v[108:109], v[104:105] neg_lo:[0,1] neg_hi:[0,1]
	v_pk_add_f32 v[110:111], v[110:111], v[106:107] neg_lo:[0,1] neg_hi:[0,1]
	v_pk_fma_f32 v[88:89], v[12:13], v[108:109], v[104:105]
	v_pk_fma_f32 v[90:91], v[14:15], v[110:111], v[106:107]
	v_lshlrev_b32_e64 v104, 16, v42
	v_and_b32_e32 v105, 0xffff0000, v42
	v_lshlrev_b32_e64 v106, 16, v43
	v_and_b32_e32 v107, 0xffff0000, v43
	v_lshlrev_b32_e64 v108, 16, v48
	v_and_b32_e32 v109, 0xffff0000, v48
	v_lshlrev_b32_e64 v110, 16, v49
	v_and_b32_e32 v111, 0xffff0000, v49
	v_pk_add_f32 v[108:109], v[108:109], v[104:105] neg_lo:[0,1] neg_hi:[0,1]
	v_pk_add_f32 v[110:111], v[110:111], v[106:107] neg_lo:[0,1] neg_hi:[0,1]
	v_pk_fma_f32 v[92:93], v[4:5], v[108:109], v[104:105]
	v_pk_fma_f32 v[94:95], v[6:7], v[110:111], v[106:107]
	v_lshlrev_b32_e64 v96, 16, v50
	v_and_b32_e32 v97, 0xffff0000, v50
	v_lshlrev_b32_e64 v98, 16, v51
	v_and_b32_e32 v99, 0xffff0000, v51
	v_lshlrev_b32_e64 v100, 16, v52
	v_and_b32_e32 v101, 0xffff0000, v52
	v_lshlrev_b32_e64 v102, 16, v53
	v_and_b32_e32 v103, 0xffff0000, v53
	v_pk_mul_f32 v[112:113], v[8:9], v[88:89]
	v_pk_mul_f32 v[114:115], v[10:11], v[90:91]
	v_pk_mul_f32 v[104:105], v[112:113], v[112:113]
	v_pk_fma_f32 v[104:105], v[114:115], v[114:115], v[104:105]
	v_add_f32_e64 v104, v104, v105
	v_pk_add_f32 v[116:117], v[100:101], -1.0 op_sel_hi:[1,0]
	v_pk_add_f32 v[118:119], v[102:103], -1.0 op_sel_hi:[1,0]
	v_add_f32_dpp v104, v104, v104 quad_perm:[1,0,3,2] row_mask:0xf bank_mask:0xf bound_ctrl:1
	v_pk_fma_f32 v[116:117], v[16:17], v[116:117], 1.0 op_sel_hi:[1,1,0]
	v_pk_fma_f32 v[118:119], v[18:19], v[118:119], 1.0 op_sel_hi:[1,1,0]
	v_add_f32_dpp v104, v104, v104 quad_perm:[2,3,0,1] row_mask:0xf bank_mask:0xf bound_ctrl:1
	v_pk_mul_f32 v[116:117], v[116:117], v[88:89]
	v_pk_mul_f32 v[118:119], v[118:119], v[90:91]
	v_add_f32_dpp v104, v104, v104 row_half_mirror row_mask:0xf bank_mask:0xf bound_ctrl:1
	ds_write_b128 v80, v[84:87] offset:24576
	ds_write_b128 v80, v[96:99] offset:24832
	v_add_f32_dpp v104, v104, v104 row_mirror row_mask:0xf bank_mask:0xf bound_ctrl:1
	v_rsq_f32_e64 v104, v104
	ds_write_b128 v80, v[116:119] offset:25088
	v_min_f32_e32 v104, 0x5368d4a5, v104
	v_pk_mul_f32 v[112:113], v[112:113], v[104:105] op_sel_hi:[1,0] neg_lo:[0,1] neg_hi:[0,1]
	v_pk_mul_f32 v[114:115], v[114:115], v[104:105] op_sel_hi:[1,0] neg_lo:[0,1] neg_hi:[0,1]
	ds_write_b128 v80, v[112:115] offset:25344
	v_pk_mul_f32 v[108:109], v[112:113], v[100:101] neg_lo:[1,0] neg_hi:[1,0]
	v_pk_mul_f32 v[110:111], v[114:115], v[102:103] neg_lo:[1,0] neg_hi:[1,0]
	ds_write_b128 v80, v[108:111] offset:25600
	ds_write_b128 v80, v[92:95] offset:25856
	s_branch .LBB0_704
